# softmax row-sum with four independent accumulators instead of two dependent add chains
# baseline (speedup 1.0000x reference)
.LBB0_447:
	s_or_b64 exec, exec, s[0:1]
	s_mov_b64 s[0:1], s[86:87]
	s_waitcnt lgkmcnt(0)
	s_barrier
	s_load_dwordx2 s[0:1], s[86:87], 0xa8
	s_mov_b32 s15, m0
	v_and_b32_e32 v1, 63, v0
	v_and_b32_e32 v2, 31, v0
	v_bfe_u32 v3, v0, 5, 1
	v_readfirstlane_b32 s18, v0
	v_mov_b32_e32 v15, 0x7f7f7f7f
	s_nop 3
	s_lshr_b32 s18, s18, 6
	s_lshl_b32 s14, s18, 10
	v_lshrrev_b32_e32 v13, 2, v1
	s_and_b32 s19, s18, 3
	s_lshl_b32 s19, s19, 4
	v_add_u32_e32 v13, s19, v13
	v_mul_u32_u24_e32 v4, 0xc0, v13
	v_lshrrev_b32_e32 v14, 4, v1
	v_xor_b32_e32 v14, v14, v1
	v_and_b32_e32 v14, 3, v14
	v_lshlrev_b32_e32 v14, 4, v14
	s_lshr_b32 s20, s18, 2
	s_lshl_b32 s20, s20, 6
	v_add3_u32 v4, v4, v14, s20
	v_add_u32_e32 v247, 0x40, v4
	v_add_u32_e32 v5, 0x80, v4
	v_lshrrev_b32_e32 v13, 2, v1
	s_lshl_b32 s19, s18, 4
	v_add_u32_e32 v13, s19, v13
	v_mul_u32_u24_e32 v13, 0x2000, v13
	v_add_u32_e32 v6, v13, v14
	v_bfe_u32 v13, v2, 2, 1
	v_lshlrev_b32_e32 v13, 5, v13
	v_and_b32_e32 v14, 3, v2
	v_add_u32_e32 v13, v13, v14
	v_lshrrev_b32_e32 v14, 3, v2
	v_lshl_add_u32 v13, v14, 2, v13
	v_lshlrev_b32_e32 v13, 6, v13
	v_lshlrev_b32_e32 v246, 1, v3
	v_xor_b32_e32 v246, v246, v14
	v_lshl_add_u32 v7, v246, 4, v13
	v_xor_b32_e32 v8, 16, v7
	v_bfe_u32 v13, v2, 2, 2
	v_lshlrev_b32_e32 v14, 1, v3
	v_xor_b32_e32 v13, v13, v14
	v_lshlrev_b32_e32 v13, 4, v13
	v_lshl_add_u32 v9, v2, 6, v13
	v_add_u32_e32 v9, 0xc000, v9
	v_xor_b32_e32 v10, 16, v9
	s_lshl_b32 s19, s18, 5
	v_add_u32_e32 v13, s19, v2
	v_mul_u32_u24_e32 v240, 0xc00, v13
	v_lshl_add_u32 v240, v3, 5, v240
	v_lshlrev_b32_e32 v241, 11, v13
	v_lshl_add_u32 v241, v3, 2, v241
	s_mov_b32 s12, 0
	s_waitcnt lgkmcnt(0)

.Latt_sk2_a:
	v_add_u32_e32 v244, s21, v9
	v_add_u32_e32 v245, s21, v10
	s_waitcnt lgkmcnt(10)
	v_mfma_f32_32x32x64_f8f6f4 v[32:47], v[152:159], v[128:135], v[16:31]
	ds_read_b128 v[200:203], v244 offset:0
	ds_read_b128 v[204:207], v245 offset:0
	s_waitcnt lgkmcnt(10)
	v_mfma_f32_32x32x64_f8f6f4 v[48:63], v[176:183], v[128:135], v[16:31]
	ds_read_b128 v[208:211], v244 offset:2048
	ds_read_b128 v[212:215], v245 offset:2048
	s_waitcnt lgkmcnt(10)
	v_mfma_f32_32x32x64_f8f6f4 v[32:47], v[160:167], v[136:143], v[32:47]
	ds_read_b128 v[216:219], v244 offset:4096
	ds_read_b128 v[220:223], v245 offset:4096
	s_waitcnt lgkmcnt(10)
	v_mfma_f32_32x32x64_f8f6f4 v[48:63], v[184:191], v[136:143], v[48:63]
	ds_read_b128 v[224:227], v244 offset:6144
	ds_read_b128 v[228:231], v245 offset:6144
	s_waitcnt lgkmcnt(10)
	v_mfma_f32_32x32x64_f8f6f4 v[32:47], v[168:175], v[144:151], v[32:47]
	s_waitcnt lgkmcnt(8)
	v_mfma_f32_32x32x64_f8f6f4 v[48:63], v[192:199], v[144:151], v[48:63]
	s_nop 15
	s_nop 3
	v_exp_f32_e32 v32, v32
	v_exp_f32_e32 v33, v33
	v_exp_f32_e32 v34, v34
	v_exp_f32_e32 v35, v35
	v_exp_f32_e32 v36, v36
	v_exp_f32_e32 v37, v37
	v_exp_f32_e32 v38, v38
	v_exp_f32_e32 v39, v39
	v_add_f32_e32 v12, v32, v34
	v_add_f32_e32 v13, v33, v35
	v_exp_f32_e32 v40, v40
	v_exp_f32_e32 v41, v41
	v_exp_f32_e32 v42, v42
	v_exp_f32_e32 v43, v43
	v_add_f32_e32 v12, v12, v36
	v_add_f32_e32 v13, v13, v37
	v_add_f32_e32 v12, v12, v38
	v_add_f32_e32 v13, v13, v39
	v_exp_f32_e32 v44, v44
	v_exp_f32_e32 v45, v45
	v_exp_f32_e32 v46, v46
	v_exp_f32_e32 v47, v47
	v_add_f32_e32 v12, v12, v40
	v_add_f32_e32 v13, v13, v41
	v_add_f32_e32 v12, v12, v42
	v_add_f32_e32 v13, v13, v43
	v_exp_f32_e32 v48, v48
	v_exp_f32_e32 v49, v49
	v_exp_f32_e32 v50, v50
	v_exp_f32_e32 v51, v51
	v_add_f32_e32 v12, v12, v44
	v_add_f32_e32 v13, v13, v45
	v_add_f32_e32 v12, v12, v46
	v_add_f32_e32 v13, v13, v47
	v_exp_f32_e32 v52, v52
	v_exp_f32_e32 v53, v53
	v_exp_f32_e32 v54, v54
	v_exp_f32_e32 v55, v55
	v_add_f32_e32 v14, v48, v50
	v_add_f32_e32 v248, v49, v51
	v_exp_f32_e32 v56, v56
	v_exp_f32_e32 v57, v57
	v_exp_f32_e32 v58, v58
	v_exp_f32_e32 v59, v59
	v_add_f32_e32 v14, v14, v52
	v_add_f32_e32 v248, v248, v53
	v_add_f32_e32 v14, v14, v54
	v_add_f32_e32 v248, v248, v55
	v_exp_f32_e32 v60, v60
	v_exp_f32_e32 v61, v61
	v_exp_f32_e32 v62, v62
	v_exp_f32_e32 v63, v63
	v_add_f32_e32 v14, v14, v56
	v_add_f32_e32 v248, v248, v57
	v_add_f32_e32 v14, v14, v58
	v_add_f32_e32 v248, v248, v59
	v_add_f32_e32 v14, v14, v60
	v_add_f32_e32 v248, v248, v61
	v_add_f32_e32 v14, v14, v62
	v_add_f32_e32 v248, v248, v63
	v_add_f32_e32 v12, v12, v13
	v_add_f32_e32 v14, v14, v248
	v_add_f32_e32 v12, v12, v14
	v_mov_b32_e32 v14, v12
	s_nop 1
	v_permlane32_swap_b32_e32 v12, v14
	v_add_f32_e32 v12, v12, v14
	v_cmp_nge_f32_e32 vcc, s16, v12
	s_cbranch_vccnz .Latt_rare_a
	v_add_f32_e32 v11, v11, v12

.Latt_b_w:
	s_waitcnt vmcnt(2) lgkmcnt(0)
	s_barrier
	s_and_b32 s19, s13, 3
	s_mul_i32 s20, s19, 0x3000
	s_add_u32 s19, s13, 3
	s_and_b32 s19, s19, 3
	s_lshl_b32 s21, s19, 13
	s_add_u32 s19, s13, 2
	s_and_b32 s19, s19, 3
	s_mul_i32 s23, s19, 0x3000
	s_add_i32 s23, s23, s14
	s_lshl_b32 s24, s19, 13
	s_add_i32 s24, s24, s14
	s_add_i32 s24, s24, 0xc000
	v_add_u32_e32 v244, s21, v9
	v_add_u32_e32 v245, s21, v10
	ds_read_b128 v[200:203], v244 offset:0
	ds_read_b128 v[204:207], v245 offset:0
	ds_read_b128 v[208:211], v244 offset:2048
	ds_read_b128 v[212:215], v245 offset:2048
	ds_read_b128 v[216:219], v244 offset:4096
	ds_read_b128 v[220:223], v245 offset:4096
	ds_read_b128 v[224:227], v244 offset:6144
	ds_read_b128 v[228:231], v245 offset:6144
	v_add_u32_e32 v242, s20, v7
	v_add_u32_e32 v243, s20, v8
	v_exp_f32_e32 v32, v32
	v_exp_f32_e32 v33, v33
	v_exp_f32_e32 v34, v34
	v_exp_f32_e32 v35, v35
	v_exp_f32_e32 v36, v36
	v_exp_f32_e32 v37, v37
	v_exp_f32_e32 v38, v38
	v_exp_f32_e32 v39, v39
	v_add_f32_e32 v12, v32, v34
	v_add_f32_e32 v13, v33, v35
	v_exp_f32_e32 v40, v40
	v_exp_f32_e32 v41, v41
	v_exp_f32_e32 v42, v42
	v_exp_f32_e32 v43, v43
	v_add_f32_e32 v12, v12, v36
	v_add_f32_e32 v13, v13, v37
	v_add_f32_e32 v12, v12, v38
	v_add_f32_e32 v13, v13, v39
	v_exp_f32_e32 v44, v44
	v_exp_f32_e32 v45, v45
	v_exp_f32_e32 v46, v46
	v_exp_f32_e32 v47, v47
	v_add_f32_e32 v12, v12, v40
	v_add_f32_e32 v13, v13, v41
	v_add_f32_e32 v12, v12, v42
	v_add_f32_e32 v13, v13, v43
	v_exp_f32_e32 v48, v48
	v_exp_f32_e32 v49, v49
	v_exp_f32_e32 v50, v50
	v_exp_f32_e32 v51, v51
	v_add_f32_e32 v12, v12, v44
	v_add_f32_e32 v13, v13, v45
	v_add_f32_e32 v12, v12, v46
	v_add_f32_e32 v13, v13, v47
	v_exp_f32_e32 v52, v52
	v_exp_f32_e32 v53, v53
	v_exp_f32_e32 v54, v54
	v_exp_f32_e32 v55, v55
	v_add_f32_e32 v14, v48, v50
	v_add_f32_e32 v248, v49, v51
	v_exp_f32_e32 v56, v56
	v_exp_f32_e32 v57, v57
	v_exp_f32_e32 v58, v58
	v_exp_f32_e32 v59, v59
	v_add_f32_e32 v14, v14, v52
	v_add_f32_e32 v248, v248, v53
	v_add_f32_e32 v14, v14, v54
	v_add_f32_e32 v248, v248, v55
	v_exp_f32_e32 v60, v60
	v_exp_f32_e32 v61, v61
	v_exp_f32_e32 v62, v62
	v_exp_f32_e32 v63, v63
	v_add_f32_e32 v14, v14, v56
	v_add_f32_e32 v248, v248, v57
	v_add_f32_e32 v14, v14, v58
	v_add_f32_e32 v248, v248, v59
	v_add_f32_e32 v14, v14, v60
	v_add_f32_e32 v248, v248, v61
	v_add_f32_e32 v14, v14, v62
	v_add_f32_e32 v248, v248, v63
	v_add_f32_e32 v12, v12, v13
	v_add_f32_e32 v14, v14, v248
	v_add_f32_e32 v12, v12, v14
	v_mov_b32_e32 v14, v12
	s_nop 1
	v_permlane32_swap_b32_e32 v12, v14
	v_add_f32_e32 v12, v12, v14
	v_cmp_nge_f32_e32 vcc, s16, v12
	s_cbranch_vccnz .Latt_rare_b
	v_add_f32_e32 v11, v11, v12

.Latt_sk2_b:
	s_waitcnt lgkmcnt(12)
	v_mfma_f32_32x32x64_f8f6f4 v[112:127], v[224:231], v[232:239], v[112:127]
	s_waitcnt lgkmcnt(10)
	v_mfma_f32_32x32x64_f8f6f4 v[32:47], v[152:159], v[128:135], v[16:31]
	s_waitcnt lgkmcnt(8)
	v_mfma_f32_32x32x64_f8f6f4 v[48:63], v[176:183], v[128:135], v[16:31]
	s_waitcnt lgkmcnt(6)
	v_mfma_f32_32x32x64_f8f6f4 v[32:47], v[160:167], v[136:143], v[32:47]
	s_waitcnt lgkmcnt(4)
	v_mfma_f32_32x32x64_f8f6f4 v[48:63], v[184:191], v[136:143], v[48:63]
	s_waitcnt lgkmcnt(2)
	v_mfma_f32_32x32x64_f8f6f4 v[32:47], v[168:175], v[144:151], v[32:47]
	s_waitcnt lgkmcnt(0)
	v_mfma_f32_32x32x64_f8f6f4 v[48:63], v[192:199], v[144:151], v[48:63]
	s_add_u32 s13, s13, 1
	s_cmp_lt_u32 s13, 128
	s_cbranch_scc1 .Latt_b_loop
	s_mov_b32 s19, 3
	s_lshl_b32 s21, s19, 13
	v_add_u32_e32 v244, s21, v9
	v_add_u32_e32 v245, s21, v10
	ds_read_b128 v[200:203], v244 offset:0
	ds_read_b128 v[204:207], v245 offset:0
	ds_read_b128 v[208:211], v244 offset:2048
	ds_read_b128 v[212:215], v245 offset:2048
	ds_read_b128 v[216:219], v244 offset:4096
	ds_read_b128 v[220:223], v245 offset:4096
	ds_read_b128 v[224:227], v244 offset:6144
	ds_read_b128 v[228:231], v245 offset:6144
	s_nop 9
	v_exp_f32_e32 v32, v32
	v_exp_f32_e32 v33, v33
	v_exp_f32_e32 v34, v34
	v_exp_f32_e32 v35, v35
	v_exp_f32_e32 v36, v36
	v_exp_f32_e32 v37, v37
	v_exp_f32_e32 v38, v38
	v_exp_f32_e32 v39, v39
	v_add_f32_e32 v12, v32, v34
	v_add_f32_e32 v13, v33, v35
	v_exp_f32_e32 v40, v40
	v_exp_f32_e32 v41, v41
	v_exp_f32_e32 v42, v42
	v_exp_f32_e32 v43, v43
	v_add_f32_e32 v12, v12, v36
	v_add_f32_e32 v13, v13, v37
	v_add_f32_e32 v12, v12, v38
	v_add_f32_e32 v13, v13, v39
	v_exp_f32_e32 v44, v44
	v_exp_f32_e32 v45, v45
	v_exp_f32_e32 v46, v46
	v_exp_f32_e32 v47, v47
	v_add_f32_e32 v12, v12, v40
	v_add_f32_e32 v13, v13, v41
	v_add_f32_e32 v12, v12, v42
	v_add_f32_e32 v13, v13, v43
	v_exp_f32_e32 v48, v48
	v_exp_f32_e32 v49, v49
	v_exp_f32_e32 v50, v50
	v_exp_f32_e32 v51, v51
	v_add_f32_e32 v12, v12, v44
	v_add_f32_e32 v13, v13, v45
	v_add_f32_e32 v12, v12, v46
	v_add_f32_e32 v13, v13, v47
	v_exp_f32_e32 v52, v52
	v_exp_f32_e32 v53, v53
	v_exp_f32_e32 v54, v54
	v_exp_f32_e32 v55, v55
	v_add_f32_e32 v14, v48, v50
	v_add_f32_e32 v248, v49, v51
	v_exp_f32_e32 v56, v56
	v_exp_f32_e32 v57, v57
	v_exp_f32_e32 v58, v58
	v_exp_f32_e32 v59, v59
	v_add_f32_e32 v14, v14, v52
	v_add_f32_e32 v248, v248, v53
	v_add_f32_e32 v14, v14, v54
	v_add_f32_e32 v248, v248, v55
	v_exp_f32_e32 v60, v60
	v_exp_f32_e32 v61, v61
	v_exp_f32_e32 v62, v62
	v_exp_f32_e32 v63, v63
	v_add_f32_e32 v14, v14, v56
	v_add_f32_e32 v248, v248, v57
	v_add_f32_e32 v14, v14, v58
	v_add_f32_e32 v248, v248, v59
	v_add_f32_e32 v14, v14, v60
	v_add_f32_e32 v248, v248, v61
	v_add_f32_e32 v14, v14, v62
	v_add_f32_e32 v248, v248, v63
	v_add_f32_e32 v12, v12, v13
	v_add_f32_e32 v14, v14, v248
	v_add_f32_e32 v12, v12, v14
	v_mov_b32_e32 v14, v12
	s_nop 1
	v_permlane32_swap_b32_e32 v12, v14
	v_add_f32_e32 v12, v12, v14
	v_cmp_nge_f32_e32 vcc, s16, v12
	s_cbranch_vccnz .Latt_rare_bt
	v_add_f32_e32 v11, v11, v12
